# NA attention: first-half bias reads made unconditional in groups of four with one LDS wait per group (was an exec-masked read plus full drain per slot)
# speedup vs baseline: 1.0154x; 1.0154x over previous
.LBB0_1705:
	s_add_i32 s90, s14, 2
	v_add_u32_e32 v0, s2, v231
	ds_read_b64_tr_b16 v[194:195], v0 offset:24576
	ds_read_b64_tr_b16 v[196:197], v0 offset:25088
	s_waitcnt lgkmcnt(9)
	v_mfma_f32_32x32x16_bf16 v[96:111], v[190:193], v[142:145], 0
	v_add_f32_e32 v2, v64, v65
	v_add_f32_e32 v2, v66, v2
	v_add_f32_e32 v2, v67, v2
	v_add_f32_e32 v2, v68, v2
	v_add_f32_e32 v2, v69, v2
	v_cvt_pk_bf16_f32 v158, v64, v65
	v_cvt_pk_bf16_f32 v159, v66, v67
	ds_read_b64_tr_b16 v[10:11], v0 offset:28672
	ds_read_b64_tr_b16 v[12:13], v0 offset:29184
	s_waitcnt lgkmcnt(10)
	v_mfma_f32_32x32x16_bf16 v[114:129], v[182:185], v[142:145], 0
	v_add_f32_e32 v2, v70, v2
	v_add_f32_e32 v2, v71, v2
	v_add_f32_e32 v2, v72, v2
	v_add_f32_e32 v6, v73, v2
	v_cvt_pk_bf16_f32 v160, v68, v69
	v_cvt_pk_bf16_f32 v161, v70, v71
	ds_read_b64_tr_b16 v[2:3], v0 offset:25600
	ds_read_b64_tr_b16 v[4:5], v0 offset:26112
	s_waitcnt lgkmcnt(11)
	v_mfma_f32_32x32x16_bf16 v[96:111], v[186:189], v[138:141], v[96:111]
	v_add_f32_e32 v6, v74, v6
	v_add_f32_e32 v6, v75, v6
	v_add_f32_e32 v6, v76, v6
	v_add_f32_e32 v14, v77, v6
	v_cvt_pk_bf16_f32 v154, v72, v73
	v_cvt_pk_bf16_f32 v155, v74, v75
	ds_read_b64_tr_b16 v[6:7], v0 offset:29696
	ds_read_b64_tr_b16 v[8:9], v0 offset:30208
	s_waitcnt lgkmcnt(12)
	v_mfma_f32_32x32x16_bf16 v[114:129], v[178:181], v[138:141], v[114:129]
	v_add_f32_e32 v14, v78, v14
	v_add_f32_e32 v14, v79, v14
	v_add_f32_e32 v14, v80, v14
	v_add_f32_e32 v14, v81, v14
	v_cvt_pk_bf16_f32 v156, v76, v77
	v_cvt_pk_bf16_f32 v157, v78, v79
	ds_read_b64_tr_b16 v[178:179], v0 offset:26624
	ds_read_b64_tr_b16 v[180:181], v0 offset:27136
	s_waitcnt lgkmcnt(13)
	v_mfma_f32_32x32x16_bf16 v[96:111], v[174:177], v[134:137], v[96:111]
	v_add_f32_e32 v14, v82, v14
	v_add_f32_e32 v14, v83, v14
	v_add_f32_e32 v14, v84, v14
	v_add_f32_e32 v14, v85, v14
	v_cvt_pk_bf16_f32 v150, v80, v81
	v_cvt_pk_bf16_f32 v151, v82, v83
	ds_read_b64_tr_b16 v[174:175], v0 offset:30720
	ds_read_b64_tr_b16 v[176:177], v0 offset:31232
	s_waitcnt lgkmcnt(14)
	v_mfma_f32_32x32x16_bf16 v[114:129], v[170:173], v[134:137], v[114:129]
	v_add_f32_e32 v14, v86, v14
	v_add_f32_e32 v14, v87, v14
	v_add_f32_e32 v14, v88, v14
	v_add_f32_e32 v14, v89, v14
	v_cvt_pk_bf16_f32 v152, v84, v85
	v_cvt_pk_bf16_f32 v153, v86, v87
	ds_read_b64_tr_b16 v[170:171], v0 offset:27648
	ds_read_b64_tr_b16 v[172:173], v0 offset:28160
	s_waitcnt lgkmcnt(14)
	v_mfma_f32_32x32x16_bf16 v[96:111], v[166:169], v[130:133], v[96:111]
	v_add_f32_e32 v14, v90, v14
	v_add_f32_e32 v14, v91, v14
	v_add_f32_e32 v14, v92, v14
	v_add_f32_e32 v14, v93, v14
	v_cvt_pk_bf16_f32 v146, v88, v89
	v_cvt_pk_bf16_f32 v147, v90, v91
	ds_read_b64_tr_b16 v[166:167], v0 offset:31744
	ds_read_b64_tr_b16 v[168:169], v0 offset:32256
	v_mfma_f32_32x32x16_bf16 v[114:129], v[162:165], v[130:133], v[114:129]
	v_add_f32_e32 v0, v94, v14
	v_add_f32_e32 v0, v95, v0
	v_add_f32_e32 v0, 0, v0
	v_cvt_pk_bf16_f32 v148, v92, v93
	v_cvt_pk_bf16_f32 v149, v94, v95
	s_add_i32 s7, s14, 5
	s_cmp_lt_i32 s7, s0
	s_cselect_b32 s2, s7, s12
	s_cmp_gt_i32 s7, s6
	s_cselect_b32 s9, s95, 0
	s_cselect_b32 s8, s13, 0
	s_lshl_b64 s[10:11], s[2:3], 18
	v_lshl_add_u64 v[14:15], v[214:215], 0, s[10:11]
	s_add_i32 s2, s15, s97
	v_lshl_add_u64 v[14:15], s[8:9], 1, v[14:15]
	s_mov_b32 s7, m0
	s_mov_b32 m0, s2
	s_nop 0
	global_load_lds_dwordx4 v[14:15], off
	s_mov_b32 m0, s7
	s_add_i32 s2, s14, 3
	s_cmp_ge_i32 s2, s0
	s_cselect_b64 s[34:35], -1, 0
	s_cmp_lt_i32 s2, s0
	s_cselect_b32 s2, s2, s12
	s_cmp_ge_i32 s90, s6
	s_cselect_b64 s[36:37], -1, 0
	s_cmp_lt_i32 s90, s6
	s_cselect_b32 s9, 0, s95
	s_cselect_b32 s8, 0, s13
	s_lshl_b64 s[10:11], s[2:3], 18
	v_lshl_add_u64 v[14:15], v[216:217], 0, s[10:11]
	s_add_i32 s2, s89, s92
	v_lshl_add_u64 v[14:15], s[8:9], 1, v[14:15]
	s_mov_b32 s7, m0
	s_mov_b32 m0, s2
	s_nop 0
	global_load_lds_dwordx4 v[14:15], off
	s_mov_b32 m0, s7
	s_cmp_gt_i32 s90, s6
	s_cselect_b64 s[8:9], -1, 0
	v_pk_add_f32 v[112:113], v[96:97], v[218:219] op_sel_hi:[1,0] neg_lo:[0,1] neg_hi:[0,1]
	v_pk_add_f32 v[96:97], v[114:115], v[218:219] op_sel_hi:[1,0] neg_lo:[0,1] neg_hi:[0,1]
	v_pk_add_f32 v[114:115], v[98:99], v[218:219] op_sel_hi:[1,0] neg_lo:[0,1] neg_hi:[0,1]
	v_pk_add_f32 v[98:99], v[116:117], v[218:219] op_sel_hi:[1,0] neg_lo:[0,1] neg_hi:[0,1]
	v_pk_add_f32 v[116:117], v[100:101], v[218:219] op_sel_hi:[1,0] neg_lo:[0,1] neg_hi:[0,1]
	v_pk_add_f32 v[100:101], v[118:119], v[218:219] op_sel_hi:[1,0] neg_lo:[0,1] neg_hi:[0,1]
	v_pk_add_f32 v[118:119], v[102:103], v[218:219] op_sel_hi:[1,0] neg_lo:[0,1] neg_hi:[0,1]
	v_pk_add_f32 v[102:103], v[120:121], v[218:219] op_sel_hi:[1,0] neg_lo:[0,1] neg_hi:[0,1]
	v_pk_add_f32 v[120:121], v[104:105], v[218:219] op_sel_hi:[1,0] neg_lo:[0,1] neg_hi:[0,1]
	v_pk_add_f32 v[104:105], v[122:123], v[218:219] op_sel_hi:[1,0] neg_lo:[0,1] neg_hi:[0,1]
	v_pk_add_f32 v[122:123], v[106:107], v[218:219] op_sel_hi:[1,0] neg_lo:[0,1] neg_hi:[0,1]
	v_pk_add_f32 v[106:107], v[124:125], v[218:219] op_sel_hi:[1,0] neg_lo:[0,1] neg_hi:[0,1]
	v_pk_add_f32 v[124:125], v[108:109], v[218:219] op_sel_hi:[1,0] neg_lo:[0,1] neg_hi:[0,1]
	v_pk_add_f32 v[108:109], v[126:127], v[218:219] op_sel_hi:[1,0] neg_lo:[0,1] neg_hi:[0,1]
	v_pk_add_f32 v[126:127], v[110:111], v[218:219] op_sel_hi:[1,0] neg_lo:[0,1] neg_hi:[0,1]
	v_pk_add_f32 v[110:111], v[128:129], v[218:219] op_sel_hi:[1,0] neg_lo:[0,1] neg_hi:[0,1]
	s_mov_b64 s[10:11], -1
	s_and_b64 vcc, exec, s[8:9]
	s_cbranch_vccnz .LBB0_1742
	s_add_i32 s2, s96, s14
	s_add_i32 s2, s2, 2
	s_cmp_lt_u32 s2, s93
	s_cselect_b64 s[10:11], -1, 0
	s_cmp_gt_u32 s2, s1
	s_cselect_b64 vcc, -1, 0
	s_or_b64 s[10:11], s[10:11], vcc
	s_and_b64 vcc, exec, s[10:11]
	s_cbranch_vccnz .LBB0_1740
	v_cndmask_b32_e64 v14, 0, v208, s[42:43]
	v_lshl_add_u32 v14, v14, 2, 0
	v_add_u32_e32 v14, 0x15000, v14
	ds_read_b32 v14, v14
	v_mov_b32_e32 v65, 0xc6ea6000
	v_mov_b32_e32 v64, 0xc6ea6000
	ds_read_b32 v235, v207
	v_add_u32_e32 v15, 1, v208
	v_cndmask_b32_e64 v15, 0, v15, s[46:47]
	v_lshl_add_u32 v15, v15, 2, 0
	v_add_u32_e32 v15, 0x15000, v15
	ds_read_b32 v15, v15
	ds_read_b32 v236, v207 offset:4
	v_add_u32_e32 v17, 2, v208
	v_cndmask_b32_e64 v17, 0, v17, s[50:51]
	v_lshl_add_u32 v17, v17, 2, 0
	v_add_u32_e32 v17, 0x15000, v17
	ds_read_b32 v17, v17
	v_mov_b32_e32 v67, 0xc6ea6000
	v_mov_b32_e32 v66, 0xc6ea6000
	ds_read_b32 v237, v207 offset:8
	v_add_u32_e32 v18, 3, v208
	v_cndmask_b32_e64 v18, 0, v18, s[54:55]
	v_lshl_add_u32 v18, v18, 2, 0
	v_add_u32_e32 v18, 0x15000, v18
	ds_read_b32 v18, v18
	ds_read_b32 v238, v207 offset:12
	s_waitcnt lgkmcnt(0)
	v_add_f32_e32 v251, v112, v235
	v_cndmask_b32_e64 v64, v64, v251, s[40:41]
	v_add_f32_e32 v251, v113, v236
	v_cndmask_b32_e64 v65, v65, v251, s[44:45]
	v_add_f32_e32 v251, v114, v237
	v_cndmask_b32_e64 v66, v66, v251, s[48:49]
	v_add_f32_e32 v251, v115, v238
	v_cndmask_b32_e64 v67, v67, v251, s[52:53]
	v_add_u32_e32 v19, 8, v208
	v_cndmask_b32_e64 v19, 0, v19, s[58:59]
	v_lshl_add_u32 v19, v19, 2, 0
	v_add_u32_e32 v19, 0x15000, v19
	ds_read_b32 v19, v19
	v_mov_b32_e32 v69, 0xc6ea6000
	v_mov_b32_e32 v68, 0xc6ea6000
	ds_read_b32 v239, v207 offset:32
	v_add_u32_e32 v20, 9, v208
	v_cndmask_b32_e64 v20, 0, v20, s[62:63]
	v_lshl_add_u32 v20, v20, 2, 0
	v_add_u32_e32 v20, 0x15000, v20
	ds_read_b32 v20, v20
	ds_read_b32 v240, v207 offset:36
	v_add_u32_e32 v21, 10, v208
	v_cndmask_b32_e64 v21, 0, v21, s[66:67]
	v_lshl_add_u32 v21, v21, 2, 0
	v_add_u32_e32 v21, 0x15000, v21
	ds_read_b32 v21, v21
	v_mov_b32_e32 v71, 0xc6ea6000
	v_mov_b32_e32 v70, 0xc6ea6000
	ds_read_b32 v241, v207 offset:40
	v_add_u32_e32 v22, 11, v208
	v_cndmask_b32_e64 v22, 0, v22, s[70:71]
	v_lshl_add_u32 v22, v22, 2, 0
	v_add_u32_e32 v22, 0x15000, v22
	ds_read_b32 v22, v22
	ds_read_b32 v242, v207 offset:44
	s_waitcnt lgkmcnt(0)
	v_add_f32_e32 v251, v116, v239
	v_cndmask_b32_e64 v68, v68, v251, s[56:57]
	v_add_f32_e32 v251, v117, v240
	v_cndmask_b32_e64 v69, v69, v251, s[60:61]
	v_add_f32_e32 v251, v118, v241
	v_cndmask_b32_e64 v70, v70, v251, s[64:65]
	v_add_f32_e32 v251, v119, v242
	v_cndmask_b32_e64 v71, v71, v251, s[68:69]
	v_add_u32_e32 v23, 16, v208
	v_cndmask_b32_e64 v23, 0, v23, s[72:73]
	v_lshl_add_u32 v23, v23, 2, 0
	v_add_u32_e32 v23, 0x15000, v23
	ds_read_b32 v23, v23
	v_mov_b32_e32 v73, 0xc6ea6000
	v_mov_b32_e32 v72, 0xc6ea6000
	ds_read_b32 v243, v207 offset:64
	v_add_u32_e32 v24, 17, v208
	v_cndmask_b32_e64 v24, 0, v24, s[74:75]
	v_lshl_add_u32 v24, v24, 2, 0
	v_add_u32_e32 v24, 0x15000, v24
	ds_read_b32 v24, v24
	ds_read_b32 v244, v207 offset:68
	v_add_u32_e32 v25, 18, v208
	v_cndmask_b32_e64 v25, 0, v25, s[76:77]
	v_lshl_add_u32 v25, v25, 2, 0
	v_add_u32_e32 v25, 0x15000, v25
	ds_read_b32 v25, v25
	v_mov_b32_e32 v75, 0xc6ea6000
	v_mov_b32_e32 v74, 0xc6ea6000
	ds_read_b32 v245, v207 offset:72
	v_add_u32_e32 v26, 19, v208
	v_cndmask_b32_e64 v26, 0, v26, s[78:79]
	v_lshl_add_u32 v26, v26, 2, 0
	v_add_u32_e32 v26, 0x15000, v26
	ds_read_b32 v26, v26
	ds_read_b32 v246, v207 offset:76
	s_waitcnt lgkmcnt(0)
	v_add_f32_e32 v251, v120, v243
	v_cndmask_b32_e64 v72, v72, v251, s[16:17]
	v_add_f32_e32 v251, v121, v244
	v_cndmask_b32_e64 v73, v73, v251, s[18:19]
	v_add_f32_e32 v251, v122, v245
	v_cndmask_b32_e64 v74, v74, v251, s[20:21]
	v_add_f32_e32 v251, v123, v246
	v_cndmask_b32_e64 v75, v75, v251, s[22:23]
	v_add_u32_e32 v27, 24, v208
	v_cndmask_b32_e64 v27, 0, v27, s[80:81]
	v_lshl_add_u32 v27, v27, 2, 0
	v_add_u32_e32 v27, 0x15000, v27
	ds_read_b32 v27, v27
	v_mov_b32_e32 v77, 0xc6ea6000
	v_mov_b32_e32 v76, 0xc6ea6000
	ds_read_b32 v247, v207 offset:96
	v_add_u32_e32 v28, 25, v208
	v_cndmask_b32_e64 v28, 0, v28, s[82:83]
	v_lshl_add_u32 v28, v28, 2, 0
	v_add_u32_e32 v28, 0x15000, v28
	ds_read_b32 v28, v28
	ds_read_b32 v248, v207 offset:100
	v_add_u32_e32 v29, 26, v208
	v_cndmask_b32_e64 v29, 0, v29, s[84:85]
	v_lshl_add_u32 v29, v29, 2, 0
	v_add_u32_e32 v29, 0x15000, v29
	ds_read_b32 v29, v29
	v_mov_b32_e32 v79, 0xc6ea6000
	v_mov_b32_e32 v78, 0xc6ea6000
	ds_read_b32 v249, v207 offset:104
	v_add_u32_e32 v30, 27, v208
	v_cndmask_b32_e64 v30, 0, v30, s[86:87]
	v_lshl_add_u32 v30, v30, 2, 0
	v_add_u32_e32 v30, 0x15000, v30
	ds_read_b32 v30, v30
	ds_read_b32 v250, v207 offset:108
	s_waitcnt lgkmcnt(0)
	v_add_f32_e32 v251, v124, v247
	v_cndmask_b32_e64 v76, v76, v251, s[24:25]
	v_add_f32_e32 v251, v125, v248
	v_cndmask_b32_e64 v77, v77, v251, s[26:27]
	v_add_f32_e32 v251, v126, v249
	v_cndmask_b32_e64 v78, v78, v251, s[28:29]
	v_add_f32_e32 v251, v127, v250
	v_cndmask_b32_e64 v79, v79, v251, s[30:31]
	s_waitcnt lgkmcnt(14)
	v_add_f32_e32 v14, v96, v14
	v_cndmask_b32_e64 v80, v16, v14, s[42:43]
	v_add_f32_e32 v14, v97, v15
	v_cndmask_b32_e64 v81, v16, v14, s[46:47]
	s_waitcnt lgkmcnt(13)
	v_add_f32_e32 v14, v98, v17
	v_cndmask_b32_e64 v82, v16, v14, s[50:51]
	s_waitcnt lgkmcnt(12)
	v_add_f32_e32 v14, v99, v18
	v_cndmask_b32_e64 v83, v16, v14, s[54:55]
	s_waitcnt lgkmcnt(11)
	v_add_f32_e32 v14, v100, v19
	v_cndmask_b32_e64 v84, v16, v14, s[58:59]
	s_waitcnt lgkmcnt(10)
	v_add_f32_e32 v14, v101, v20
	v_cndmask_b32_e64 v85, v16, v14, s[62:63]
	s_waitcnt lgkmcnt(9)
	v_add_f32_e32 v14, v102, v21
	v_cndmask_b32_e64 v86, v16, v14, s[66:67]
	s_waitcnt lgkmcnt(8)
	v_add_f32_e32 v14, v103, v22
	v_cndmask_b32_e64 v87, v16, v14, s[70:71]
	s_waitcnt lgkmcnt(7)
	v_add_f32_e32 v14, v104, v23
	v_cndmask_b32_e64 v88, v16, v14, s[72:73]
	s_waitcnt lgkmcnt(6)
	v_add_f32_e32 v14, v105, v24
	v_cndmask_b32_e64 v89, v16, v14, s[74:75]
	s_waitcnt lgkmcnt(5)
	v_add_f32_e32 v14, v106, v25
	v_cndmask_b32_e64 v90, v16, v14, s[76:77]
	s_waitcnt lgkmcnt(4)
	v_add_f32_e32 v14, v107, v26
	v_cndmask_b32_e64 v91, v16, v14, s[78:79]
	s_waitcnt lgkmcnt(3)
	v_add_f32_e32 v14, v108, v27
	v_cndmask_b32_e64 v92, v16, v14, s[80:81]
	s_waitcnt lgkmcnt(2)
	v_add_f32_e32 v14, v109, v28
	v_cndmask_b32_e64 v93, v16, v14, s[82:83]
	s_waitcnt lgkmcnt(1)
	v_add_f32_e32 v14, v110, v29
	v_cndmask_b32_e64 v94, v16, v14, s[84:85]
	s_waitcnt lgkmcnt(0)
	v_add_f32_e32 v14, v111, v30
	v_cndmask_b32_e64 v95, v16, v14, s[86:87]
	s_branch .LBB0_1741

.LBB0_1753:
	s_add_i32 s2, s96, s14
	s_add_i32 s2, s2, 3
	s_cmp_lt_u32 s2, s93
	s_cselect_b64 s[8:9], -1, 0
	s_cmp_gt_u32 s2, s1
	s_cselect_b64 s[10:11], -1, 0
	s_or_b64 s[8:9], s[8:9], s[10:11]
	s_and_b64 vcc, exec, s[8:9]
	s_cbranch_vccnz .LBB0_1788
	v_add_u32_e32 v17, 31, v208
	v_cndmask_b32_e64 v17, 0, v17, s[42:43]
	v_lshl_add_u32 v17, v17, 2, 0
	v_add_u32_e32 v17, 0x15000, v17
	ds_read_b32 v17, v17
	v_mov_b32_e32 v65, 0xc6ea6000
	v_mov_b32_e32 v64, 0xc6ea6000
	ds_read_b32 v235, v207 offset:124
	v_add_u32_e32 v18, 32, v208
	v_cndmask_b32_e64 v18, 0, v18, s[46:47]
	v_lshl_add_u32 v18, v18, 2, 0
	v_add_u32_e32 v18, 0x15000, v18
	ds_read_b32 v18, v18
	ds_read_b32 v236, v207 offset:128
	v_add_u32_e32 v19, 33, v208
	v_cndmask_b32_e64 v19, 0, v19, s[50:51]
	v_lshl_add_u32 v19, v19, 2, 0
	v_add_u32_e32 v19, 0x15000, v19
	ds_read_b32 v19, v19
	v_mov_b32_e32 v67, 0xc6ea6000
	v_mov_b32_e32 v66, 0xc6ea6000
	ds_read_b32 v237, v207 offset:132
	v_add_u32_e32 v20, 34, v208
	v_cndmask_b32_e64 v20, 0, v20, s[54:55]
	v_lshl_add_u32 v20, v20, 2, 0
	v_add_u32_e32 v20, 0x15000, v20
	ds_read_b32 v20, v20
	ds_read_b32 v238, v207 offset:136
	s_waitcnt lgkmcnt(0)
	v_add_f32_e32 v251, v112, v235
	v_cndmask_b32_e64 v64, v64, v251, s[40:41]
	v_add_f32_e32 v251, v113, v236
	v_cndmask_b32_e64 v65, v65, v251, s[44:45]
	v_add_f32_e32 v251, v114, v237
	v_cndmask_b32_e64 v66, v66, v251, s[48:49]
	v_add_f32_e32 v251, v115, v238
	v_cndmask_b32_e64 v67, v67, v251, s[52:53]
	v_add_u32_e32 v21, 39, v208
	v_cndmask_b32_e64 v21, 0, v21, s[58:59]
	v_lshl_add_u32 v21, v21, 2, 0
	v_add_u32_e32 v21, 0x15000, v21
	ds_read_b32 v21, v21
	v_mov_b32_e32 v69, 0xc6ea6000
	v_mov_b32_e32 v68, 0xc6ea6000
	ds_read_b32 v239, v207 offset:156
	v_add_u32_e32 v22, 40, v208
	v_cndmask_b32_e64 v22, 0, v22, s[62:63]
	v_lshl_add_u32 v22, v22, 2, 0
	v_add_u32_e32 v22, 0x15000, v22
	ds_read_b32 v22, v22
	ds_read_b32 v240, v207 offset:160
	v_add_u32_e32 v23, 41, v208
	v_cndmask_b32_e64 v23, 0, v23, s[66:67]
	v_lshl_add_u32 v23, v23, 2, 0
	v_add_u32_e32 v23, 0x15000, v23
	ds_read_b32 v23, v23
	v_mov_b32_e32 v71, 0xc6ea6000
	v_mov_b32_e32 v70, 0xc6ea6000
	ds_read_b32 v241, v207 offset:164
	v_add_u32_e32 v24, 42, v208
	v_cndmask_b32_e64 v24, 0, v24, s[70:71]
	v_lshl_add_u32 v24, v24, 2, 0
	v_add_u32_e32 v24, 0x15000, v24
	ds_read_b32 v24, v24
	ds_read_b32 v242, v207 offset:168
	s_waitcnt lgkmcnt(0)
	v_add_f32_e32 v251, v116, v239
	v_cndmask_b32_e64 v68, v68, v251, s[56:57]
	v_add_f32_e32 v251, v117, v240
	v_cndmask_b32_e64 v69, v69, v251, s[60:61]
	v_add_f32_e32 v251, v118, v241
	v_cndmask_b32_e64 v70, v70, v251, s[64:65]
	v_add_f32_e32 v251, v119, v242
	v_cndmask_b32_e64 v71, v71, v251, s[68:69]
	v_add_u32_e32 v25, 47, v208
	v_cndmask_b32_e64 v25, 0, v25, s[72:73]
	v_lshl_add_u32 v25, v25, 2, 0
	v_add_u32_e32 v25, 0x15000, v25
	ds_read_b32 v25, v25
	v_mov_b32_e32 v73, 0xc6ea6000
	v_mov_b32_e32 v72, 0xc6ea6000
	ds_read_b32 v243, v207 offset:188
	v_add_u32_e32 v26, 48, v208
	v_cndmask_b32_e64 v26, 0, v26, s[74:75]
	v_lshl_add_u32 v26, v26, 2, 0
	v_add_u32_e32 v26, 0x15000, v26
	ds_read_b32 v26, v26
	ds_read_b32 v244, v207 offset:192
	v_add_u32_e32 v27, 49, v208
	v_cndmask_b32_e64 v27, 0, v27, s[76:77]
	v_lshl_add_u32 v27, v27, 2, 0
	v_add_u32_e32 v27, 0x15000, v27
	ds_read_b32 v27, v27
	v_mov_b32_e32 v75, 0xc6ea6000
	v_mov_b32_e32 v74, 0xc6ea6000
	ds_read_b32 v245, v207 offset:196
	v_add_u32_e32 v28, 50, v208
	v_cndmask_b32_e64 v28, 0, v28, s[78:79]
	v_lshl_add_u32 v28, v28, 2, 0
	v_add_u32_e32 v28, 0x15000, v28
	ds_read_b32 v28, v28
	ds_read_b32 v246, v207 offset:200
	s_waitcnt lgkmcnt(0)
	v_add_f32_e32 v251, v120, v243
	v_cndmask_b32_e64 v72, v72, v251, s[16:17]
	v_add_f32_e32 v251, v121, v244
	v_cndmask_b32_e64 v73, v73, v251, s[18:19]
	v_add_f32_e32 v251, v122, v245
	v_cndmask_b32_e64 v74, v74, v251, s[20:21]
	v_add_f32_e32 v251, v123, v246
	v_cndmask_b32_e64 v75, v75, v251, s[22:23]
	v_add_u32_e32 v29, 55, v208
	v_cndmask_b32_e64 v29, 0, v29, s[80:81]
	v_lshl_add_u32 v29, v29, 2, 0
	v_add_u32_e32 v29, 0x15000, v29
	ds_read_b32 v29, v29
	v_mov_b32_e32 v77, 0xc6ea6000
	v_mov_b32_e32 v76, 0xc6ea6000
	ds_read_b32 v247, v207 offset:220
	v_add_u32_e32 v30, 56, v208
	v_cndmask_b32_e64 v30, 0, v30, s[82:83]
	v_lshl_add_u32 v30, v30, 2, 0
	v_add_u32_e32 v30, 0x15000, v30
	ds_read_b32 v30, v30
	ds_read_b32 v248, v207 offset:224
	v_add_u32_e32 v31, 57, v208
	v_cndmask_b32_e64 v31, 0, v31, s[84:85]
	v_lshl_add_u32 v31, v31, 2, 0
	v_add_u32_e32 v31, 0x15000, v31
	ds_read_b32 v31, v31
	v_mov_b32_e32 v79, 0xc6ea6000
	v_mov_b32_e32 v78, 0xc6ea6000
	ds_read_b32 v249, v207 offset:228
	v_add_u32_e32 v80, 58, v208
	v_cndmask_b32_e64 v80, 0, v80, s[86:87]
	v_lshl_add_u32 v80, v80, 2, 0
	v_add_u32_e32 v80, 0x15000, v80
	ds_read_b32 v95, v80
	ds_read_b32 v250, v207 offset:232
	s_waitcnt lgkmcnt(0)
	v_add_f32_e32 v251, v124, v247
	v_cndmask_b32_e64 v76, v76, v251, s[24:25]
	v_add_f32_e32 v251, v125, v248
	v_cndmask_b32_e64 v77, v77, v251, s[26:27]
	v_add_f32_e32 v251, v126, v249
	v_cndmask_b32_e64 v78, v78, v251, s[28:29]
	v_add_f32_e32 v251, v127, v250
	v_cndmask_b32_e64 v79, v79, v251, s[30:31]
	s_waitcnt lgkmcnt(14)
	v_add_f32_e32 v17, v96, v17
	v_cndmask_b32_e64 v80, v16, v17, s[42:43]
	v_add_f32_e32 v17, v97, v18
	v_cndmask_b32_e64 v81, v16, v17, s[46:47]
	s_waitcnt lgkmcnt(13)
	v_add_f32_e32 v17, v98, v19
	v_cndmask_b32_e64 v82, v16, v17, s[50:51]
	s_waitcnt lgkmcnt(12)
	v_add_f32_e32 v17, v99, v20
	v_cndmask_b32_e64 v83, v16, v17, s[54:55]
	s_waitcnt lgkmcnt(11)
	v_add_f32_e32 v17, v100, v21
	v_cndmask_b32_e64 v84, v16, v17, s[58:59]
	s_waitcnt lgkmcnt(10)
	v_add_f32_e32 v17, v101, v22
	v_cndmask_b32_e64 v85, v16, v17, s[62:63]
	s_waitcnt lgkmcnt(9)
	v_add_f32_e32 v17, v102, v23
	v_cndmask_b32_e64 v86, v16, v17, s[66:67]
	s_waitcnt lgkmcnt(8)
	v_add_f32_e32 v17, v103, v24
	v_cndmask_b32_e64 v87, v16, v17, s[70:71]
	s_waitcnt lgkmcnt(7)
	v_add_f32_e32 v17, v104, v25
	v_cndmask_b32_e64 v88, v16, v17, s[72:73]
	s_waitcnt lgkmcnt(6)
	v_add_f32_e32 v17, v105, v26
	v_cndmask_b32_e64 v89, v16, v17, s[74:75]
	s_waitcnt lgkmcnt(5)
	v_add_f32_e32 v17, v106, v27
	v_cndmask_b32_e64 v90, v16, v17, s[76:77]
	s_waitcnt lgkmcnt(4)
	v_add_f32_e32 v17, v107, v28
	v_cndmask_b32_e64 v91, v16, v17, s[78:79]
	s_waitcnt lgkmcnt(3)
	v_add_f32_e32 v17, v108, v29
	v_cndmask_b32_e64 v92, v16, v17, s[80:81]
	s_waitcnt lgkmcnt(2)
	v_add_f32_e32 v17, v109, v30
	v_cndmask_b32_e64 v93, v16, v17, s[82:83]
	s_waitcnt lgkmcnt(1)
	v_add_f32_e32 v17, v110, v31
	v_cndmask_b32_e64 v94, v16, v17, s[84:85]
	s_waitcnt lgkmcnt(0)
	v_add_f32_e32 v17, v111, v95
	v_cndmask_b32_e64 v95, v16, v17, s[86:87]
	s_branch .LBB0_1789
